# sc_conv: all taps loads issued together (one wait per item, weights hoisted); gdn_scan: group-B DMA issued after the first MFMA ladder
# speedup vs baseline: 1.0287x; 1.0078x over previous
; DI unsigned pk_bf16(float a, float b) { bf2_t v = __builtin_convertvector((f2_t){a, b}, bf2_t); return __builtin_bit_cast(unsigned, v); }
; DI float bf_lo(unsigned u) { return __uint_as_float(u << 16); }
; DI float bf_hi(unsigned u) { return __uint_as_float(u & 0xffff0000u); }
; DI u32x2 pack4(const f32x4 a) { u32x2 w; w.x = pk_bf16(a[0], a[1]); w.y = pk_bf16(a[2], a[3]); return w; }
; DI void gdn_scan(const Params& P, int item, unsigned char* smem) {
;     ...
;     for (int c = 0; c < 128; ++c) {
;         if (c + 1 < 128) SC_ISSUE(c + 1);
;         const unsigned char* sg = smem + (c & 1) * SC_STAGE;
;         f32x4 aP = {0.f, 0.f, 0.f, 0.f}, aO = {0.f, 0.f, 0.f, 0.f};
; #pragma unroll
;         for (int kk = 0; kk < 4; ++kk) {
;             const bf16x8 sf = *(const bf16x8*)(ST + (16 * nt + r16) * 136 + 32 * kk + 8 * q4);
;             const int co = (((4 * kk + q4) ^ r16) << 4);
;             const bf16x8 wf = *(const bf16x8*)(sg + SC_W + ow + co);
;             const bf16x8 qd = *(const bf16x8*)(sg + SC_QD + ow + co);
;             aP = __builtin_amdgcn_mfma_f32_16x16x32_bf16(wf, sf, aP, 0, 0, 0);
;             aO = __builtin_amdgcn_mfma_f32_16x16x32_bf16(qd, sf, aO, 0, 0, 0);
;         }
;         {
;             const u32x2 uu = *(const u32x2*)(sg + out);
;             f32x4 vn;
;             vn[0] = bf_lo(uu.x) - aP[0]; vn[1] = bf_hi(uu.x) - aP[1]; vn[2] = bf_lo(uu.y) - aP[2]; vn[3] = bf_hi(uu.y) - aP[3];
;             *(u32x2*)(VT + (16 * nt + r16) * 72 + 16 * mi + 4 * q4) = pack4(vn);
;         }
;         lds_barrier();
; #pragma unroll
;         for (int ks = 0; ks < 2; ++ks) {
;             const bf16x8 vf = *(const bf16x8*)(VT + (16 * nt + r16) * 72 + 32 * ks + 8 * q4);
;             const bf16x8 qk = *(const bf16x8*)(sg + oqk + (((4 * ks + q4) ^ x8) << 4));
;             aO = __builtin_amdgcn_mfma_f32_16x16x32_bf16(qk, vf, aO, 0, 0, 0);
;         }
;         {
;             bf16_t* op = mixed + (tb + (size_t)c * 64 + 16 * mi + 4 * q4) * D + 256 + h * 128 + ns * 32 + 16 * nt + r16;
; #pragma unroll
;             for (int r = 0; r < 4; ++r) op[(size_t)r * D] = (bf16_t)(pk_bf16(aO[r], 0.f) & 0xffffu);
;         }
;         const float gl = gls[c];
;         bf16x8 kd[2];
; #pragma unroll
;         for (int ks = 0; ks < 2; ++ks) kd[ks] = *(const bf16x8*)(sg + okd + (((4 * ks + q4) ^ x8) << 4));
.LBB0_74:
	s_add_i32 s11, s17, 1
	s_bitcmp1_b32 s17, 0
	s_cselect_b32 s17, 0xf000, 0
	v_add_u32_e32 v41, s17, v34
	v_add_u32_e32 v50, v41, v37
	v_add_u32_e32 v51, v41, v36
	v_add_u32_e32 v52, v41, v35
	v_add_u32_e32 v53, v41, v33
	v_add3_u32 v54, s17, v31, v32
	ds_read_b128 v[64:67], v40
	ds_read_b128 v[68:71], v50
	ds_read_b128 v[72:75], v50 offset:16384
	ds_read_b128 v[76:79], v40 offset:64
	ds_read_b128 v[80:83], v51
	ds_read_b128 v[84:87], v51 offset:16384
	ds_read_b128 v[88:91], v40 offset:128
	ds_read_b128 v[92:95], v52
	ds_read_b128 v[96:99], v52 offset:16384
	ds_read_b128 v[100:103], v40 offset:192
	ds_read_b128 v[104:107], v53
	ds_read_b128 v[108:111], v53 offset:16384
	ds_read_b64 v[62:63], v54 offset:57344
	s_waitcnt lgkmcnt(11)
	v_mfma_f32_16x16x32_bf16 v[46:49], v[68:71], v[64:67], 0
	s_waitcnt lgkmcnt(10)
	v_mfma_f32_16x16x32_bf16 v[42:45], v[72:75], v[64:67], 0
	s_waitcnt lgkmcnt(8)
	v_mfma_f32_16x16x32_bf16 v[46:49], v[80:83], v[76:79], v[46:49]
	s_waitcnt lgkmcnt(7)
	v_mfma_f32_16x16x32_bf16 v[42:45], v[84:87], v[76:79], v[42:45]
	s_waitcnt lgkmcnt(5)
	v_mfma_f32_16x16x32_bf16 v[46:49], v[92:95], v[88:91], v[46:49]
	s_waitcnt lgkmcnt(4)
	v_mfma_f32_16x16x32_bf16 v[42:45], v[96:99], v[88:91], v[42:45]
	s_waitcnt lgkmcnt(2)
	v_mfma_f32_16x16x32_bf16 v[46:49], v[104:107], v[100:103], v[46:49]
	s_waitcnt lgkmcnt(1)
	v_mfma_f32_16x16x32_bf16 v[42:45], v[108:111], v[100:103], v[42:45]
	s_sub_i32 s18, 0xf000, s17
	s_add_i32 s18, s18, s16
	s_add_i32 s18, s18, 0x8000
	s_mov_b32 m0, s18
	s_mov_b64 s[22:23], 0x38000
	v_lshl_add_u64 v[56:57], v[18:19], 0, s[4:5]
	global_load_lds_dwordx4 v[22:23], off
	s_add_u32 m0, m0, 0x2000
	v_lshl_add_u64 v[58:59], v[56:57], 0, s[22:23]
	global_load_lds_dwordx4 v[56:57], off
	s_add_u32 m0, m0, 0x2000
	s_nop 0
	global_load_lds_dwordx4 v[58:59], off
	s_waitcnt lgkmcnt(0)
	v_lshlrev_b32_e32 v52, 16, v62
	v_and_b32_e32 v53, 0xffff0000, v62
	v_lshlrev_b32_e32 v50, 16, v63
	v_and_b32_e32 v51, 0xffff0000, v63
	v_add_u32_e32 v41, v39, v38
	v_add_u32_e32 v54, s17, v29
	v_add_u32_e32 v55, s17, v9
	s_nop 3
	v_pk_add_f32 v[46:47], v[52:53], v[46:47] neg_lo:[0,1] neg_hi:[0,1]
	v_pk_add_f32 v[48:49], v[50:51], v[48:49] neg_lo:[0,1] neg_hi:[0,1]
	v_cvt_pk_bf16_f32 v46, v46, v47
	v_cvt_pk_bf16_f32 v47, v48, v49
	ds_write_b64 v30, v[46:47]
	v_add_u32_e32 v50, v54, v26
	v_add_u32_e32 v51, v54, v24
	v_add_u32_e32 v52, v55, v26
	v_add_u32_e32 v53, v55, v24
	v_mov_b32_e32 v61, s10
	s_waitcnt vmcnt(12)
	s_waitcnt lgkmcnt(0)
	s_barrier
	ds_read_b128 v[64:67], v41
	ds_read_b128 v[68:71], v50 offset:32768
	ds_read_b128 v[72:75], v41 offset:64
	ds_read_b128 v[76:79], v51 offset:32768
	ds_read_b32 v60, v61
	ds_read_b128 v[80:83], v52 offset:40960
	ds_read_b128 v[84:87], v28
	ds_read_b128 v[88:91], v53 offset:40960
	ds_read_b128 v[92:95], v28 offset:64
	ds_read_b128 v[96:99], v28 offset:2304
	ds_read_b128 v[100:103], v28 offset:2368
	s_cmpk_eq_i32 s11, 0x7f
	s_cbranch_scc1 .Lsc_noA
	s_mov_b64 s[18:19], 0x70000
	v_lshl_add_u64 v[20:21], v[20:21], 0, s[18:19]
	s_mov_b64 s[18:19], 0x30000
	v_lshl_add_u64 v[14:15], v[14:15], 0, s[18:19]
	v_lshl_add_u64 v[16:17], v[16:17], 0, s[18:19]
	s_add_i32 s18, s16, s17
	s_mov_b32 m0, s18
	s_mov_b64 s[22:23], 0x38000
	s_mov_b64 s[20:21], 0x18000
	v_lshl_add_u64 v[56:57], v[20:21], 0, s[4:5]
	v_lshl_add_u64 v[58:59], v[56:57], 0, s[22:23]
	global_load_lds_dwordx4 v[56:57], off
	s_add_u32 m0, m0, 0x2000
	v_lshl_add_u64 v[56:57], v[14:15], 0, s[4:5]
	global_load_lds_dwordx4 v[58:59], off
	s_add_u32 m0, m0, 0x2000
	v_lshl_add_u64 v[58:59], v[56:57], 0, s[20:21]
	global_load_lds_dwordx4 v[56:57], off
	s_add_u32 m0, m0, 0x2000
	s_nop 0
	global_load_lds_dwordx4 v[58:59], off
	s_andn2_b64 vcc, exec, s[8:9]
	s_cbranch_vccnz .Lscl_nou
	s_add_u32 m0, m0, 0x8000
	s_nop 0
	global_load_lds_dwordx4 v[16:17], off
	s_branch .Lscl_ud

; DI unsigned pk_bf16(float a, float b) { bf2_t v = __builtin_convertvector((f2_t){a, b}, bf2_t); return __builtin_bit_cast(unsigned, v); }
; DI float bf_lo(unsigned u) { return __uint_as_float(u << 16); }
; DI float bf_hi(unsigned u) { return __uint_as_float(u & 0xffff0000u); }
; DI void sc_conv(const Params& P, int l, int vb, int nvb) {
;     ...
;     for (size_t it = (size_t)vb * NTHREADS + tids; it < (size_t)NTOK * 128; it += (size_t)nvb * NTHREADS) {
;         const int t = (int)(it >> 7), c = (int)(it & 127) * 2;
;         const int s = t & (SEQ - 1);
;         float y0 = 0.f, y1 = 0.f;
; #pragma unroll
;         for (int i = 0; i < 3; ++i) {
;             if (s - 2 + i >= 0) {
;                 const bf16_t* pr = proj + (size_t)(t - 2 + i) * PJ;
;                 const unsigned cu = *(const unsigned*)(pr + 3072 + c), hu = *(const unsigned*)(pr + 3328 + c);
;                 y0 += w[i * 256 + c] * (bf_lo(cu) * bf_lo(hu));
;                 y1 += w[i * 256 + c + 1] * (bf_hi(cu) * bf_hi(hu));
;             }
;         }
;         const unsigned bu = *(const unsigned*)(proj + (size_t)t * PJ + 2816 + c);
;         *(unsigned*)(mixed + (size_t)t * D + 768 + c) = pk_bf16(bf_lo(bu) * y0, bf_hi(bu) * y1);
;     }
.LBB0_81:
	s_or_b64 exec, exec, s[6:7]
	v_mov_b32_e32 v2, v223
	v_readlane_b32 s8, v250, 32
	v_readlane_b32 s9, v250, 33
	v_ashrrev_i32_e32 v3, 31, v2
	s_cmp_eq_u32 s52, 3
	v_lshl_add_u64 v[0:1], s[8:9], 0, v[2:3]
	s_mov_b64 s[8:9], 0x400000
	s_cselect_b64 s[6:7], -1, 0
	v_cmp_gt_u64_e32 vcc, s[8:9], v[0:1]
	s_and_saveexec_b64 s[8:9], vcc
	s_cbranch_execz .LBB0_88
	s_and_b64 s[10:11], s[6:7], exec
	v_readlane_b32 s12, v250, 58
	s_cselect_b32 s4, 0, 0xc00
	v_readlane_b32 s18, v249, 0
	v_readlane_b32 s0, v249, 47
	v_readlane_b32 s13, v250, 59
	v_readlane_b32 s19, v249, 1
	s_add_u32 s10, s18, s4
	v_readlane_b32 s1, v249, 48
	s_addc_u32 s11, s19, 0
	s_mov_b64 s[12:13], 0
	v_lshl_add_u64 v[2:3], v[2:3], 1, s[0:1]
	v_readlane_b32 s14, v250, 60
	v_readlane_b32 s15, v250, 61
	v_readlane_b32 s16, v250, 62
	v_readlane_b32 s17, v250, 63
	v_readlane_b32 s20, v249, 2
	v_readlane_b32 s21, v249, 3
	v_readlane_b32 s22, v249, 4
	v_readlane_b32 s23, v249, 5
	v_readlane_b32 s24, v249, 6
	v_readlane_b32 s25, v249, 7
	v_readlane_b32 s26, v249, 8
	v_readlane_b32 s27, v249, 9
	v_and_b32_e32 v5, 0xfe, v2
	v_lshlrev_b32_e32 v10, 2, v5
	v_lshlrev_b32_e32 v4, 1, v5
	v_mov_b32_e32 v5, v177
	global_load_dwordx2 v[20:21], v10, s[10:11]
	global_load_dwordx2 v[22:23], v10, s[10:11] offset:1024
	global_load_dwordx2 v[24:25], v10, s[10:11] offset:2048
	v_readlane_b32 s0, v250, 34
	v_readlane_b32 s1, v250, 35
	s_mov_b32 s16, 0xffffe400
	s_mov_b32 s17, -1
.LBB0_84:
	v_alignbit_b32 v11, v1, v0, 7
	v_lshrrev_b64 v[6:7], 7, v[0:1]
	v_and_b32_e32 v26, 0x1fff, v11
	v_mov_b64_e32 v[12:13], s[58:59]
	v_mad_u64_u32 v[12:13], s[14:15], v11, s33, v[12:13]
	v_lshl_add_u64 v[12:13], v[12:13], 0, v[4:5]
	v_add_co_u32_e32 v12, vcc, 0x1000, v12
	v_lshlrev_b64 v[6:7], 11, v[6:7]
	v_mov_b32_e32 v27, 0
	v_addc_co_u32_e32 v13, vcc, 0, v13, vcc
	v_mov_b32_e32 v28, 0
	v_lshl_add_u64 v[14:15], v[12:13], 0, s[16:17]
	v_mov_b32_e32 v29, 0
	v_lshl_add_u64 v[16:17], v[14:15], 0, s[16:17]
	v_mov_b32_e32 v30, 0
	global_load_dword v31, v[12:13], off offset:2048
	global_load_dword v32, v[12:13], off offset:2560
	global_load_dword v33, v[12:13], off offset:1536
	v_cmp_ne_u32_e32 vcc, 0, v26
	s_and_saveexec_b64 s[14:15], vcc
	global_load_dword v29, v[14:15], off offset:2048
	global_load_dword v30, v[14:15], off offset:2560
	s_mov_b64 exec, s[14:15]
	v_cmp_lt_u32_e32 vcc, 1, v26
	s_and_saveexec_b64 s[14:15], vcc
	global_load_dword v27, v[16:17], off offset:2048
	global_load_dword v28, v[16:17], off offset:2560
	s_mov_b64 exec, s[14:15]
	v_lshl_add_u64 v[6:7], s[90:91], 0, v[6:7]
	v_lshl_add_u64 v[18:19], v[6:7], 0, v[4:5]
	v_lshl_add_u64 v[0:1], v[0:1], 0, s[0:1]
	s_mov_b64 s[14:15], 0x3fffff
	v_cmp_lt_u64_e32 vcc, s[14:15], v[0:1]
	s_or_b64 s[12:13], vcc, s[12:13]
	v_add_co_u32_e32 v18, vcc, 0x5a00000, v18
	s_nop 1
	v_addc_co_u32_e32 v19, vcc, 0, v19, vcc
	s_waitcnt vmcnt(0)
	v_lshlrev_b32_e32 v34, 16, v27
	v_and_b32_e32 v35, 0xffff0000, v27
	v_lshlrev_b32_e32 v36, 16, v28
	v_and_b32_e32 v37, 0xffff0000, v28
	v_pk_mul_f32 v[34:35], v[34:35], v[36:37]
	v_lshlrev_b32_e32 v38, 16, v29
	v_and_b32_e32 v39, 0xffff0000, v29
	v_lshlrev_b32_e32 v36, 16, v30
	v_and_b32_e32 v37, 0xffff0000, v30
	v_pk_fma_f32 v[8:9], v[20:21], v[34:35], 0 op_sel_hi:[1,1,0]
	v_pk_mul_f32 v[38:39], v[38:39], v[36:37]
	v_lshlrev_b32_e32 v34, 16, v31
	v_and_b32_e32 v35, 0xffff0000, v31
	v_lshlrev_b32_e32 v36, 16, v32
	v_and_b32_e32 v37, 0xffff0000, v32
	v_pk_fma_f32 v[8:9], v[22:23], v[38:39], v[8:9]
	v_pk_mul_f32 v[34:35], v[34:35], v[36:37]
	v_lshlrev_b32_e32 v38, 16, v33
	v_and_b32_e32 v39, 0xffff0000, v33
	s_nop 0
	v_pk_fma_f32 v[8:9], v[24:25], v[34:35], v[8:9]
	s_nop 0
	v_pk_mul_f32 v[8:9], v[8:9], v[38:39]
	s_nop 0
	v_cvt_pk_bf16_f32 v8, v8, v9
	global_store_dword v[18:19], v8, off offset:1536
	s_andn2_b64 exec, exec, s[12:13]
	s_cbranch_execnz .LBB0_84
